# adds: G1 next-unit tile arithmetic moved from unit top into the second load segment of the peeled first K-iteration (scalar compares)
# baseline (speedup 1.0000x reference)
.LBB0_65:
	s_add_u32 s22, s22, 0x40080
	s_addc_u32 s23, s23, 0
	s_add_u32 s55, s24, 0x100
	s_addc_u32 s56, s25, 0
	s_mov_b32 s57, -2
	s_cmp_eq_u32 s50, 0
	s_cbranch_scc1 .Lrb68_skip
	s_andn2_b64 vcc, exec, s[6:7]
	s_cbranch_vccnz .Lrb68_skip
	s_barrier
.Lrb68_skip:
	s_add_u32 s24, s22, 0xfffc0080
	s_addc_u32 s25, s23, -1
	s_add_i32 s60, 0, 0x10000
	s_cmp_eq_u32 s57, 12
	s_cselect_b32 s27, s15, s25
	s_cselect_b32 s26, s21, s24
	s_cselect_b32 s25, s13, s56
	s_cselect_b32 s24, s33, s55
	s_add_i32 s63, 0, 0x14000
	v_add_u32_e32 v154, s60, v172
	v_add_u32_e32 v176, s63, v172
	ds_read_b128 v[130:133], v154
	ds_read_b128 v[146:149], v154 offset:1024
	ds_read_b128 v[150:153], v154 offset:2048
	ds_read_b128 v[154:157], v154 offset:3072
	ds_read_b128 v[158:161], v176
	ds_read_b128 v[162:165], v176 offset:1024
	ds_read_b128 v[168:171], v176 offset:2048
	ds_read_b128 v[176:179], v176 offset:3072
	v_lshl_add_u64 v[208:209], s[22:23], 0, v[142:143]
	s_add_i32 m0, s37, 0xc000
	ds_read_b128 v[180:183], v175
	ds_read_b128 v[184:187], v175 offset:1024
	ds_read_b128 v[188:191], v175 offset:2048
	ds_read_b128 v[192:195], v175 offset:3072
	ds_read_b128 v[196:199], v175 offset:4096
	ds_read_b128 v[200:203], v175 offset:5120
	ds_read_b128 v[204:207], v175 offset:6144
	ds_read_b128 v[216:219], v175 offset:7168
	global_load_lds_dwordx4 v[208:209], off
	v_lshl_add_u64 v[208:209], s[22:23], 0, v[144:145]
	s_add_i32 m0, s37, 0xe000
	s_nop 0
	global_load_lds_dwordx4 v[208:209], off
	s_waitcnt vmcnt(8)
	s_waitcnt lgkmcnt(0)
	s_barrier
	s_setprio 1
	s_waitcnt lgkmcnt(0)
	v_mfma_f32_16x16x32_f16 v[126:129], v[130:133], v[180:183], 0
	v_mfma_f32_16x16x32_f16 v[118:121], v[150:153], v[180:183], 0
	v_mfma_f32_16x16x32_f16 v[110:113], v[130:133], v[188:191], 0
	v_mfma_f32_16x16x32_f16 v[102:105], v[150:153], v[188:191], 0
	v_mfma_f32_16x16x32_f16 v[92:95], v[130:133], v[196:199], 0
	v_mfma_f32_16x16x32_f16 v[84:87], v[150:153], v[196:199], 0
	v_mfma_f32_16x16x32_f16 v[76:79], v[130:133], v[204:207], 0
	v_mfma_f32_16x16x32_f16 v[68:71], v[150:153], v[204:207], 0
	v_mfma_f32_16x16x32_f16 v[126:129], v[146:149], v[184:187], v[126:129]
	v_mfma_f32_16x16x32_f16 v[118:121], v[154:157], v[184:187], v[118:121]
	v_mfma_f32_16x16x32_f16 v[110:113], v[146:149], v[192:195], v[110:113]
	v_mfma_f32_16x16x32_f16 v[102:105], v[154:157], v[192:195], v[102:105]
	v_mfma_f32_16x16x32_f16 v[92:95], v[146:149], v[200:203], v[92:95]
	v_mfma_f32_16x16x32_f16 v[84:87], v[154:157], v[200:203], v[84:87]
	v_mfma_f32_16x16x32_f16 v[76:79], v[146:149], v[216:219], v[76:79]
	v_mfma_f32_16x16x32_f16 v[68:71], v[154:157], v[216:219], v[68:71]
	v_mfma_f32_16x16x32_f16 v[122:125], v[158:161], v[180:183], 0
	v_mfma_f32_16x16x32_f16 v[114:117], v[168:171], v[180:183], 0
	v_mfma_f32_16x16x32_f16 v[106:109], v[158:161], v[188:191], 0
	v_mfma_f32_16x16x32_f16 v[98:101], v[168:171], v[188:191], 0
	v_mfma_f32_16x16x32_f16 v[88:91], v[158:161], v[196:199], 0
	v_mfma_f32_16x16x32_f16 v[80:83], v[168:171], v[196:199], 0
	v_mfma_f32_16x16x32_f16 v[72:75], v[158:161], v[204:207], 0
	v_mfma_f32_16x16x32_f16 v[64:67], v[168:171], v[204:207], 0
	v_mfma_f32_16x16x32_f16 v[122:125], v[162:165], v[184:187], v[122:125]
	v_mfma_f32_16x16x32_f16 v[114:117], v[176:179], v[184:187], v[114:117]
	v_mfma_f32_16x16x32_f16 v[106:109], v[162:165], v[192:195], v[106:109]
	v_mfma_f32_16x16x32_f16 v[98:101], v[176:179], v[192:195], v[98:101]
	v_mfma_f32_16x16x32_f16 v[88:91], v[162:165], v[200:203], v[88:91]
	v_mfma_f32_16x16x32_f16 v[80:83], v[176:179], v[200:203], v[80:83]
	v_mfma_f32_16x16x32_f16 v[72:75], v[162:165], v[216:219], v[72:75]
	v_mfma_f32_16x16x32_f16 v[64:67], v[176:179], v[216:219], v[64:67]
	s_setprio 0
	s_barrier
	s_add_i32 s60, s60, s29
	v_lshl_add_u64 v[208:209], s[24:25], 0, v[96:97]
	s_mov_b32 m0, s60
	ds_read_b128 v[180:183], v175 offset:16384
	ds_read_b128 v[184:187], v175 offset:17408
	ds_read_b128 v[188:191], v175 offset:18432
	ds_read_b128 v[192:195], v175 offset:19456
	ds_read_b128 v[196:199], v175 offset:20480
	ds_read_b128 v[200:203], v175 offset:21504
	ds_read_b128 v[204:207], v175 offset:22528
	ds_read_b128 v[216:219], v175 offset:23552
	global_load_lds_dwordx4 v[208:209], off
	s_add_i32 m0, s60, 0x2000
	s_add_u32 s60, s24, 0x40000
	v_lshl_add_u64 v[210:211], s[24:25], 0, v[134:135]
	s_addc_u32 s61, s25, 0
	s_add_i32 s63, s63, s29
	global_load_lds_dwordx4 v[210:211], off
	v_lshl_add_u64 v[212:213], s[60:61], 0, v[96:97]
	s_mov_b32 m0, s63
	v_lshl_add_u64 v[220:221], s[26:27], 0, v[136:137]
	global_load_lds_dwordx4 v[212:213], off
	v_lshl_add_u64 v[212:213], s[60:61], 0, v[134:135]
	s_add_i32 m0, s63, 0x2000
	s_nop 0
	global_load_lds_dwordx4 v[212:213], off
	v_lshl_add_u64 v[212:213], s[26:27], 0, v[138:139]
	s_mov_b32 m0, s37
	s_nop 0
	global_load_lds_dwordx4 v[212:213], off
	s_mov_b32 m0, s45
	s_nop 0
	global_load_lds_dwordx4 v[220:221], off
	s_add_i32 s50, s50, 1
	v_readlane_b32 s13, v254, 3
	s_mul_i32 s13, s50, s13
	s_mul_hi_u32 s15, s50, s54
	s_add_i32 s15, s15, s13
	s_mul_i32 s13, s50, s54
	s_add_u32 s16, s13, s72
	s_addc_u32 s17, s15, s36
	s_cmp_lt_u32 s16, 0x1600
	s_cselect_b64 s[42:43], -1, 0
	s_cbranch_scc0 .Lh68_nn
	s_ashr_i32 s12, s16, 31
	s_lshr_b32 s12, s12, 29
	s_add_i32 s12, s16, s12
	s_ashr_i32 s13, s12, 3
	s_and_b32 s12, s12, -8
	s_sub_i32 s12, s16, s12
	s_cmp_lt_i32 s12, 0
	s_movk_i32 s14, 0x2c1
	s_cselect_b32 s14, s14, 0x2c0
	s_mul_i32 s12, s12, s14
	s_add_i32 s12, s12, s13
	s_mul_hi_i32 s13, s12, 0x2e8ba2e9
	s_lshr_b32 s14, s13, 31
	s_ashr_i32 s13, s13, 5
	s_add_i32 s13, s13, s14
	s_lshl_b32 s14, s13, 3
	s_mulk_i32 s13, 0xb0
	s_sub_i32 s13, s12, s13
	s_lshr_b32 s12, s13, 3
	s_and_b32 s13, s13, 7
	s_add_i32 s14, s14, s13
.Lh68_nn:
	s_ashr_i32 s15, s14, 31
	s_lshl_b64 s[16:17], s[14:15], 19
	s_add_u32 s16, s30, s16
	s_addc_u32 s17, s31, s17
	s_sub_u32 s21, s22, 0x40080
	s_subb_u32 s15, s23, 0
	s_cmp_lg_u64 s[42:43], 0
	s_cselect_b32 s15, s17, s15
	s_cselect_b32 s21, s16, s21
	s_ashr_i32 s13, s12, 31
	s_lshl_b64 s[18:19], s[12:13], 19
	s_add_u32 s18, s34, s18
	s_addc_u32 s19, s35, s19
	s_sub_u32 s33, s55, 0x100
	s_subb_u32 s13, s56, 0
	s_cmp_lg_u64 s[42:43], 0
	s_cselect_b32 s13, s19, s13
	s_cselect_b32 s33, s18, s33
	s_waitcnt vmcnt(8)
	s_waitcnt lgkmcnt(0)
	s_barrier
	s_setprio 1
	s_waitcnt lgkmcnt(0)
	v_mfma_f32_16x16x32_f16 v[60:63], v[130:133], v[180:183], 0
	v_mfma_f32_16x16x32_f16 v[52:55], v[150:153], v[180:183], 0
	v_mfma_f32_16x16x32_f16 v[44:47], v[130:133], v[188:191], 0
	v_mfma_f32_16x16x32_f16 v[36:39], v[150:153], v[188:191], 0
	v_mfma_f32_16x16x32_f16 v[28:31], v[130:133], v[196:199], 0
	v_mfma_f32_16x16x32_f16 v[20:23], v[150:153], v[196:199], 0
	v_mfma_f32_16x16x32_f16 v[12:15], v[130:133], v[204:207], 0
	v_mfma_f32_16x16x32_f16 v[4:7], v[150:153], v[204:207], 0
	v_mfma_f32_16x16x32_f16 v[60:63], v[146:149], v[184:187], v[60:63]
	v_mfma_f32_16x16x32_f16 v[52:55], v[154:157], v[184:187], v[52:55]
	v_mfma_f32_16x16x32_f16 v[44:47], v[146:149], v[192:195], v[44:47]
	v_mfma_f32_16x16x32_f16 v[36:39], v[154:157], v[192:195], v[36:39]
	v_mfma_f32_16x16x32_f16 v[28:31], v[146:149], v[200:203], v[28:31]
	v_mfma_f32_16x16x32_f16 v[20:23], v[154:157], v[200:203], v[20:23]
	v_mfma_f32_16x16x32_f16 v[12:15], v[146:149], v[216:219], v[12:15]
	v_mfma_f32_16x16x32_f16 v[4:7], v[154:157], v[216:219], v[4:7]
	v_mfma_f32_16x16x32_f16 v[56:59], v[158:161], v[180:183], 0
	v_mfma_f32_16x16x32_f16 v[48:51], v[168:171], v[180:183], 0
	v_mfma_f32_16x16x32_f16 v[40:43], v[158:161], v[188:191], 0
	v_mfma_f32_16x16x32_f16 v[32:35], v[168:171], v[188:191], 0
	v_mfma_f32_16x16x32_f16 v[24:27], v[158:161], v[196:199], 0
	v_mfma_f32_16x16x32_f16 v[16:19], v[168:171], v[196:199], 0
	v_mfma_f32_16x16x32_f16 v[8:11], v[158:161], v[204:207], 0
	v_mfma_f32_16x16x32_f16 v[0:3], v[168:171], v[204:207], 0
	v_mfma_f32_16x16x32_f16 v[56:59], v[162:165], v[184:187], v[56:59]
	v_mfma_f32_16x16x32_f16 v[48:51], v[176:179], v[184:187], v[48:51]
	v_mfma_f32_16x16x32_f16 v[40:43], v[162:165], v[192:195], v[40:43]
	v_mfma_f32_16x16x32_f16 v[32:35], v[176:179], v[192:195], v[32:35]
	v_mfma_f32_16x16x32_f16 v[24:27], v[162:165], v[200:203], v[24:27]
	v_mfma_f32_16x16x32_f16 v[16:19], v[176:179], v[200:203], v[16:19]
	v_mfma_f32_16x16x32_f16 v[8:11], v[162:165], v[216:219], v[8:11]
	v_mfma_f32_16x16x32_f16 v[0:3], v[176:179], v[216:219], v[0:3]
	s_setprio 0
	s_barrier
	s_add_i32 s60, 0, 0x18000
	s_add_i32 s61, 0, 0x1c000
	v_add_u32_e32 v154, s60, v172
	v_add_u32_e32 v176, s61, v172
	ds_read_b128 v[130:133], v154
	ds_read_b128 v[146:149], v154 offset:1024
	ds_read_b128 v[150:153], v154 offset:2048
	ds_read_b128 v[154:157], v154 offset:3072
	ds_read_b128 v[158:161], v176
	ds_read_b128 v[162:165], v176 offset:1024
	ds_read_b128 v[168:171], v176 offset:2048
	ds_read_b128 v[176:179], v176 offset:3072
	s_add_u32 s26, s26, 0x40000
	s_addc_u32 s27, s27, 0
	s_mov_b32 m0, s46
	v_lshl_add_u64 v[222:223], s[26:27], 0, v[138:139]
	ds_read_b128 v[180:183], v175 offset:32768
	ds_read_b128 v[184:187], v175 offset:33792
	ds_read_b128 v[188:191], v175 offset:34816
	ds_read_b128 v[192:195], v175 offset:35840
	ds_read_b128 v[196:199], v175 offset:36864
	ds_read_b128 v[200:203], v175 offset:37888
	ds_read_b128 v[204:207], v175 offset:38912
	ds_read_b128 v[216:219], v175 offset:39936
	global_load_lds_dwordx4 v[222:223], off
	v_lshl_add_u64 v[222:223], s[26:27], 0, v[136:137]
	s_mov_b32 m0, s47
	s_nop 0
	global_load_lds_dwordx4 v[222:223], off
	s_waitcnt vmcnt(8)
	s_waitcnt lgkmcnt(0)
	s_barrier
	s_setprio 1
	s_waitcnt lgkmcnt(0)
	v_mfma_f32_16x16x32_f16 v[126:129], v[130:133], v[180:183], v[126:129]
	v_mfma_f32_16x16x32_f16 v[118:121], v[150:153], v[180:183], v[118:121]
	v_mfma_f32_16x16x32_f16 v[110:113], v[130:133], v[188:191], v[110:113]
	v_mfma_f32_16x16x32_f16 v[102:105], v[150:153], v[188:191], v[102:105]
	v_mfma_f32_16x16x32_f16 v[92:95], v[130:133], v[196:199], v[92:95]
	v_mfma_f32_16x16x32_f16 v[84:87], v[150:153], v[196:199], v[84:87]
	v_mfma_f32_16x16x32_f16 v[76:79], v[130:133], v[204:207], v[76:79]
	v_mfma_f32_16x16x32_f16 v[68:71], v[150:153], v[204:207], v[68:71]
	v_mfma_f32_16x16x32_f16 v[126:129], v[146:149], v[184:187], v[126:129]
	v_mfma_f32_16x16x32_f16 v[118:121], v[154:157], v[184:187], v[118:121]
	v_mfma_f32_16x16x32_f16 v[110:113], v[146:149], v[192:195], v[110:113]
	v_mfma_f32_16x16x32_f16 v[102:105], v[154:157], v[192:195], v[102:105]
	v_mfma_f32_16x16x32_f16 v[92:95], v[146:149], v[200:203], v[92:95]
	v_mfma_f32_16x16x32_f16 v[84:87], v[154:157], v[200:203], v[84:87]
	v_mfma_f32_16x16x32_f16 v[76:79], v[146:149], v[216:219], v[76:79]
	v_mfma_f32_16x16x32_f16 v[68:71], v[154:157], v[216:219], v[68:71]
	v_mfma_f32_16x16x32_f16 v[122:125], v[158:161], v[180:183], v[122:125]
	v_mfma_f32_16x16x32_f16 v[114:117], v[168:171], v[180:183], v[114:117]
	v_mfma_f32_16x16x32_f16 v[106:109], v[158:161], v[188:191], v[106:109]
	v_mfma_f32_16x16x32_f16 v[98:101], v[168:171], v[188:191], v[98:101]
	v_mfma_f32_16x16x32_f16 v[88:91], v[158:161], v[196:199], v[88:91]
	v_mfma_f32_16x16x32_f16 v[80:83], v[168:171], v[196:199], v[80:83]
	v_mfma_f32_16x16x32_f16 v[72:75], v[158:161], v[204:207], v[72:75]
	v_mfma_f32_16x16x32_f16 v[64:67], v[168:171], v[204:207], v[64:67]
	v_mfma_f32_16x16x32_f16 v[122:125], v[162:165], v[184:187], v[122:125]
	v_mfma_f32_16x16x32_f16 v[114:117], v[176:179], v[184:187], v[114:117]
	v_mfma_f32_16x16x32_f16 v[106:109], v[162:165], v[192:195], v[106:109]
	v_mfma_f32_16x16x32_f16 v[98:101], v[176:179], v[192:195], v[98:101]
	v_mfma_f32_16x16x32_f16 v[88:91], v[162:165], v[200:203], v[88:91]
	v_mfma_f32_16x16x32_f16 v[80:83], v[176:179], v[200:203], v[80:83]
	v_mfma_f32_16x16x32_f16 v[72:75], v[162:165], v[216:219], v[72:75]
	v_mfma_f32_16x16x32_f16 v[64:67], v[176:179], v[216:219], v[64:67]
	s_setprio 0
	s_barrier
	s_add_i32 s26, s60, s29
	v_lshl_add_u64 v[208:209], v[208:209], 0, s[94:95]
	s_mov_b32 m0, s26
	ds_read_b128 v[180:183], v175 offset:49152
	ds_read_b128 v[184:187], v175 offset:50176
	ds_read_b128 v[188:191], v175 offset:51200
	ds_read_b128 v[192:195], v175 offset:52224
	ds_read_b128 v[196:199], v175 offset:53248
	ds_read_b128 v[200:203], v175 offset:54272
	ds_read_b128 v[204:207], v175 offset:55296
	ds_read_b128 v[216:219], v175 offset:56320
	global_load_lds_dwordx4 v[208:209], off
	s_add_i32 m0, s26, 0x2000
	s_add_u32 s24, s24, 0x40080
	v_lshl_add_u64 v[208:209], v[210:211], 0, s[94:95]
	s_addc_u32 s25, s25, 0
	s_add_i32 s26, s61, s29
	global_load_lds_dwordx4 v[208:209], off
	v_lshl_add_u64 v[208:209], s[24:25], 0, v[96:97]
	s_mov_b32 m0, s26
	s_nop 0
	global_load_lds_dwordx4 v[208:209], off
	v_lshl_add_u64 v[208:209], s[24:25], 0, v[134:135]
	s_add_i32 m0, s26, 0x2000
	s_nop 0
	global_load_lds_dwordx4 v[208:209], off
	v_lshl_add_u64 v[208:209], v[212:213], 0, s[94:95]
	s_mov_b32 m0, s48
	s_nop 0
	global_load_lds_dwordx4 v[208:209], off
	v_lshl_add_u64 v[208:209], v[220:221], 0, s[94:95]
	s_mov_b32 m0, s49
	s_nop 0
	global_load_lds_dwordx4 v[208:209], off
	s_waitcnt vmcnt(8)
	s_waitcnt lgkmcnt(0)
	s_barrier
	s_setprio 1
	s_waitcnt lgkmcnt(0)
	v_mfma_f32_16x16x32_f16 v[60:63], v[130:133], v[180:183], v[60:63]
	v_mfma_f32_16x16x32_f16 v[52:55], v[150:153], v[180:183], v[52:55]
	v_mfma_f32_16x16x32_f16 v[44:47], v[130:133], v[188:191], v[44:47]
	v_mfma_f32_16x16x32_f16 v[36:39], v[150:153], v[188:191], v[36:39]
	v_mfma_f32_16x16x32_f16 v[28:31], v[130:133], v[196:199], v[28:31]
	v_mfma_f32_16x16x32_f16 v[20:23], v[150:153], v[196:199], v[20:23]
	v_mfma_f32_16x16x32_f16 v[12:15], v[130:133], v[204:207], v[12:15]
	v_mfma_f32_16x16x32_f16 v[4:7], v[150:153], v[204:207], v[4:7]
	v_mfma_f32_16x16x32_f16 v[60:63], v[146:149], v[184:187], v[60:63]
	v_mfma_f32_16x16x32_f16 v[52:55], v[154:157], v[184:187], v[52:55]
	v_mfma_f32_16x16x32_f16 v[44:47], v[146:149], v[192:195], v[44:47]
	v_mfma_f32_16x16x32_f16 v[36:39], v[154:157], v[192:195], v[36:39]
	v_mfma_f32_16x16x32_f16 v[28:31], v[146:149], v[200:203], v[28:31]
	v_mfma_f32_16x16x32_f16 v[20:23], v[154:157], v[200:203], v[20:23]
	v_mfma_f32_16x16x32_f16 v[12:15], v[146:149], v[216:219], v[12:15]
	v_mfma_f32_16x16x32_f16 v[4:7], v[154:157], v[216:219], v[4:7]
	v_mfma_f32_16x16x32_f16 v[56:59], v[158:161], v[180:183], v[56:59]
	v_mfma_f32_16x16x32_f16 v[48:51], v[168:171], v[180:183], v[48:51]
	v_mfma_f32_16x16x32_f16 v[40:43], v[158:161], v[188:191], v[40:43]
	v_mfma_f32_16x16x32_f16 v[32:35], v[168:171], v[188:191], v[32:35]
	v_mfma_f32_16x16x32_f16 v[24:27], v[158:161], v[196:199], v[24:27]
	v_mfma_f32_16x16x32_f16 v[16:19], v[168:171], v[196:199], v[16:19]
	v_mfma_f32_16x16x32_f16 v[8:11], v[158:161], v[204:207], v[8:11]
	v_mfma_f32_16x16x32_f16 v[0:3], v[168:171], v[204:207], v[0:3]
	v_mfma_f32_16x16x32_f16 v[56:59], v[162:165], v[184:187], v[56:59]
	v_mfma_f32_16x16x32_f16 v[48:51], v[176:179], v[184:187], v[48:51]
	v_mfma_f32_16x16x32_f16 v[40:43], v[162:165], v[192:195], v[40:43]
	v_mfma_f32_16x16x32_f16 v[32:35], v[176:179], v[192:195], v[32:35]
	v_mfma_f32_16x16x32_f16 v[24:27], v[162:165], v[200:203], v[24:27]
	v_mfma_f32_16x16x32_f16 v[16:19], v[176:179], v[200:203], v[16:19]
	v_mfma_f32_16x16x32_f16 v[8:11], v[162:165], v[216:219], v[8:11]
	v_mfma_f32_16x16x32_f16 v[0:3], v[176:179], v[216:219], v[0:3]
	s_setprio 0
	s_barrier
	s_add_i32 s57, s57, 2
	s_add_u32 s22, s22, 0x100
	s_addc_u32 s23, s23, 0
	s_add_u32 s55, s55, 0x100
	s_addc_u32 s56, s56, 0
	s_cmp_gt_u32 s57, 13
	s_cbranch_scc0 .LBB0_68
	s_branch .Lz68_exit
